# attention: L2 warm-up touches of the next unit's first K/V tiles and Q rows during the current unit's drain, on top of v91
# baseline (speedup 1.0000x reference)
.LBB0_728:
	s_ashr_i32 s24, s56, 31
	s_lshr_b32 s25, s24, 26
	s_add_i32 s25, s56, s25
	s_ashr_i32 s28, s25, 6
	s_and_b32 s25, s25, 0xffffc0
	s_sub_i32 s40, s56, s25
	s_lshr_b32 s24, s24, 23
	s_lshr_b32 s25, s28, 29
	s_add_i32 s24, s56, s24
	s_add_i32 s25, s28, s25
	s_ashr_i32 s24, s24, 9
	s_and_b32 s25, s25, -8
	v_mov_b32_e32 v90, v201
	s_sub_i32 s44, s28, s25
	s_ashr_i32 s25, s24, 31
	v_readfirstlane_b32 s60, v90
	s_lshl_b32 s40, s40, 8
	s_ashr_i32 s57, s60, 6
	s_lshl_b64 s[28:29], s[24:25], 14
	s_ashr_i32 s41, s40, 31
	s_add_u32 s28, s28, s40
	s_addc_u32 s29, s29, s41
	s_lshl_b32 s40, s57, 5
	s_ashr_i32 s41, s40, 31
	s_add_u32 s42, s28, s40
	s_addc_u32 s43, s29, s41
	s_lshl_b64 s[28:29], s[42:43], 10
	s_add_u32 s45, s3, s28
	s_addc_u32 s46, s26, s29
	s_lshl_b32 s28, s44, 6
	s_ashr_i32 s29, s28, 31
	s_lshl_b64 s[40:41], s[28:29], 1
	s_add_u32 s62, s45, s40
	s_addc_u32 s63, s46, s41
	s_lshl_b64 s[24:25], s[24:25], 22
	s_add_u32 s45, s48, s24
	s_addc_u32 s46, s49, s25
	s_mov_b32 s98, 0xfffe00
	s_mov_b32 s99, 0x400000
	s_cmp_lt_i32 s44, 4
	s_cselect_b32 s98, 0x200, s98
	s_cselect_b32 s99, 0x80, s99
	s_add_u32 s100, s62, s98
	s_addc_u32 s101, s63, 0
	s_add_u32 s98, s45, s99
	s_addc_u32 s99, s46, 0
	s_lshl_b32 s28, s44, 4
	s_andn2_b32 s28, s28, 63
	s_ashr_i32 s29, s28, 31
	s_lshl_b64 s[28:29], s[28:29], 1
	s_add_u32 s44, s45, s28
	s_addc_u32 s45, s46, s29
	s_add_u32 s46, s50, s24
	s_addc_u32 s47, s51, s25
	v_and_b32_e32 v186, 63, v90
	s_add_u32 s58, s46, s28
	s_addc_u32 s59, s47, s29
	v_lshlrev_b32_e32 v88, 8, v186
	v_mov_b32_e32 v89, v2
	s_lshl_b32 s46, s57, 3
	v_lshl_add_u64 v[0:1], s[44:45], 0, v[88:89]
	s_ashr_i32 s47, s46, 31
	s_lshl_b32 s44, s57, 4
	v_bfe_u32 v91, v90, 2, 4
	v_lshl_add_u64 v[182:183], s[46:47], 1, v[0:1]
	v_and_or_b32 v0, s44, 48, v91
	s_ashr_i32 s44, s60, 3
	v_lshlrev_b32_e32 v0, 8, v0
	v_mov_b32_e32 v1, v2
	s_andn2_b32 s44, s44, 31
	v_lshl_add_u64 v[0:1], s[58:59], 0, v[0:1]
	s_ashr_i32 s45, s44, 31
	s_lshl_b32 s59, s57, 10
	v_lshlrev_b32_e32 v187, 3, v90
	s_cmp_lg_u32 0, -1
	v_and_b32_e32 v193, 24, v187
	s_cselect_b32 s58, 0, 0
	v_lshl_add_u64 v[0:1], s[44:45], 1, v[0:1]
	v_lshlrev_b32_e32 v4, 1, v193
	v_mov_b32_e32 v5, v2
	s_add_i32 s59, s59, s58
	s_mov_b32 s61, m0
	s_mov_b32 m0, s59
	s_nop 0
	global_load_lds_dwordx4 v[182:183], off
	s_mov_b32 m0, s61
	v_and_b32_e32 v188, 31, v90
	v_lshl_add_u64 v[180:181], v[0:1], 0, v[4:5]
	s_add_i32 s58, s59, 0x6000
	s_mov_b32 s61, m0
	s_mov_b32 m0, s58
	s_nop 0
	global_load_lds_dwordx4 v[180:181], off
	s_mov_b32 m0, s61
	v_lshl_add_u64 v[0:1], v[182:183], 0, s[34:35]
	v_bfe_u32 v189, v90, 5, 1
	s_add_i32 s61, s59, 0x2000
	s_mov_b32 s64, m0
	s_mov_b32 m0, s61
	s_nop 0
	global_load_lds_dwordx4 v[0:1], off
	s_mov_b32 m0, s64
	v_lshlrev_b32_e32 v0, 10, v188
	v_lshl_or_b32 v0, v189, 4, v0
	global_load_dwordx4 v[160:163], v0, s[62:63]
	global_load_dwordx4 v[156:159], v0, s[62:63] offset:32
	global_load_dwordx4 v[144:147], v0, s[62:63] offset:64
	global_load_dwordx4 v[136:139], v0, s[62:63] offset:96
	v_lshlrev_b32_e32 v1, 10, v189
	v_lshlrev_b32_e32 v3, 4, v188
	v_mov_b32_e32 v14, v2
	v_mov_b32_e32 v15, v2
	v_add3_u32 v191, 0, v1, v3
	v_mov_b32_e32 v0, v2
	v_mov_b32_e32 v1, v2
	v_mov_b32_e32 v3, v2
	v_mov_b32_e32 v4, v2
	v_mov_b32_e32 v6, v2
	v_mov_b32_e32 v7, v2
	v_mov_b32_e32 v8, v2
	v_mov_b32_e32 v9, v2
	v_mov_b32_e32 v10, v2
	v_mov_b32_e32 v11, v2
	v_mov_b32_e32 v12, v2
	v_mov_b32_e32 v13, v2
	v_mov_b64_e32 v[50:51], v[14:15]
	v_mov_b64_e32 v[48:49], v[12:13]
	v_mov_b64_e32 v[46:47], v[10:11]
	v_mov_b64_e32 v[44:45], v[8:9]
	v_mov_b64_e32 v[42:43], v[6:7]
	v_mov_b64_e32 v[40:41], v[4:5]
	v_mov_b64_e32 v[38:39], v[2:3]
	v_mov_b64_e32 v[36:37], v[0:1]
	v_lshl_add_u64 v[0:1], v[182:183], 0, s[36:37]
	s_add_i32 s61, s59, 0x4000
	s_mov_b32 s62, m0
	s_mov_b32 m0, s61
	s_nop 0
	global_load_lds_dwordx4 v[0:1], off
	s_mov_b32 m0, s62
	s_waitcnt vmcnt(3) lgkmcnt(0)
	s_barrier
	ds_read_b128 v[4:7], v191
	ds_read_b128 v[52:55], v191 offset:512
	v_lshl_add_u64 v[0:1], v[182:183], 0, s[76:77]
	s_add_i32 s61, s59, 0x8000
	s_cmp_gt_i32 s57, 3
	s_waitcnt vmcnt(3) lgkmcnt(1)
	v_mfma_f32_32x32x16_bf16 v[20:35], v[4:7], v[160:163], v[36:51]
	s_waitcnt lgkmcnt(0)
	v_mfma_f32_32x32x16_bf16 v[4:19], v[52:55], v[160:163], v[36:51]
	ds_read_b128 v[52:55], v191 offset:2048
	ds_read_b128 v[56:59], v191 offset:2560
	s_waitcnt vmcnt(2) lgkmcnt(1)
	v_mfma_f32_32x32x16_bf16 v[20:35], v[52:55], v[156:159], v[20:35]
	s_waitcnt lgkmcnt(0)
	v_mfma_f32_32x32x16_bf16 v[4:19], v[56:59], v[156:159], v[4:19]
	ds_read_b128 v[52:55], v191 offset:4096
	ds_read_b128 v[56:59], v191 offset:4608
	s_waitcnt vmcnt(1) lgkmcnt(1)
	v_mfma_f32_32x32x16_bf16 v[20:35], v[52:55], v[144:147], v[20:35]
	s_waitcnt lgkmcnt(0)
	v_mfma_f32_32x32x16_bf16 v[4:19], v[56:59], v[144:147], v[4:19]
	ds_read_b128 v[52:55], v191 offset:6144
	ds_read_b128 v[56:59], v191 offset:6656
	s_waitcnt vmcnt(0) lgkmcnt(1)
	v_mfma_f32_32x32x16_bf16 v[20:35], v[52:55], v[136:139], v[20:35]
	v_lshl_add_u64 v[52:53], v[180:181], 0, s[34:35]
	s_waitcnt lgkmcnt(0)
	v_mfma_f32_32x32x16_bf16 v[4:19], v[56:59], v[136:139], v[4:19]
	s_nop 15
	s_nop 7
	s_waitcnt vmcnt(0) lgkmcnt(0)
	s_barrier
	s_mov_b32 s62, m0
	s_mov_b32 m0, s59
	s_nop 0
	global_load_lds_dwordx4 v[0:1], off
	s_mov_b32 m0, s62
	s_nop 0
	s_mov_b32 s62, m0
	s_mov_b32 m0, s61
	s_nop 0
	global_load_lds_dwordx4 v[52:53], off
	s_mov_b32 m0, s62
	ds_read_b128 v[84:87], v191 offset:8192
	ds_read_b128 v[168:171], v191 offset:8704
	ds_read_b128 v[172:175], v191 offset:10240
	ds_read_b128 v[164:167], v191 offset:10752
	ds_read_b128 v[128:131], v191 offset:12288
	ds_read_b128 v[124:127], v191 offset:12800
	ds_read_b128 v[120:123], v191 offset:14336
	ds_read_b128 v[116:119], v191 offset:14848
	s_waitcnt vmcnt(2) lgkmcnt(0)
	s_barrier
	s_cbranch_scc0 .LBB0_730
	s_setprio 1

.LBB0_731:
	s_mov_b32 s44, s29
	s_mov_b32 s28, s25
	v_add_u32_e32 v195, s45, v190
	ds_read_b64_tr_b16 v[196:197], v195 offset:24576
	ds_read_b64_tr_b16 v[198:199], v195 offset:25088
	v_add_f32_e32 v88, v68, v69
	v_add_f32_e32 v88, v70, v88
	v_add_f32_e32 v88, v71, v88
	v_add_f32_e32 v88, v72, v88
	v_add_f32_e32 v88, v73, v88
	v_cvt_pk_bf16_f32 v152, v68, v69
	v_cvt_pk_bf16_f32 v153, v70, v71
	v_mfma_f32_32x32x16_bf16 v[100:115], v[84:87], v[160:163], 0
	ds_read_b64_tr_b16 v[68:69], v195 offset:28672
	ds_read_b64_tr_b16 v[70:71], v195 offset:29184
	v_add_f32_e32 v84, v74, v88
	v_add_f32_e32 v84, v75, v84
	v_add_f32_e32 v84, v76, v84
	v_add_f32_e32 v132, v77, v84
	v_mfma_f32_32x32x16_bf16 v[84:99], v[168:171], v[160:163], 0
	v_cvt_pk_bf16_f32 v154, v72, v73
	v_cvt_pk_bf16_f32 v155, v74, v75
	ds_read_b64_tr_b16 v[72:73], v195 offset:25600
	ds_read_b64_tr_b16 v[74:75], v195 offset:26112
	v_add_f32_e32 v132, v78, v132
	v_add_f32_e32 v132, v79, v132
	v_add_f32_e32 v132, v80, v132
	v_add_f32_e32 v132, v81, v132
	v_cvt_pk_bf16_f32 v148, v76, v77
	v_cvt_pk_bf16_f32 v149, v78, v79
	v_mfma_f32_32x32x16_bf16 v[100:115], v[172:175], v[156:159], v[100:115]
	ds_read_b64_tr_b16 v[76:77], v195 offset:29696
	ds_read_b64_tr_b16 v[78:79], v195 offset:30208
	v_mfma_f32_32x32x16_bf16 v[84:99], v[164:167], v[156:159], v[84:99]
	v_add_f32_e32 v132, v82, v132
	v_add_f32_e32 v132, v83, v132
	v_add_f32_e32 v132, v52, v132
	v_add_f32_e32 v132, v53, v132
	v_cvt_pk_bf16_f32 v150, v80, v81
	v_cvt_pk_bf16_f32 v151, v82, v83
	ds_read_b64_tr_b16 v[80:81], v195 offset:26624
	ds_read_b64_tr_b16 v[82:83], v195 offset:27136
	v_mfma_f32_32x32x16_bf16 v[100:115], v[128:131], v[144:147], v[100:115]
	v_add_f32_e32 v128, v54, v132
	v_add_f32_e32 v128, v55, v128
	v_add_f32_e32 v128, v56, v128
	v_add_f32_e32 v128, v57, v128
	v_cvt_pk_bf16_f32 v140, v52, v53
	v_cvt_pk_bf16_f32 v141, v54, v55
	ds_read_b64_tr_b16 v[52:53], v195 offset:30720
	ds_read_b64_tr_b16 v[54:55], v195 offset:31232
	v_mfma_f32_32x32x16_bf16 v[84:99], v[124:127], v[144:147], v[84:99]
	v_add_f32_e32 v124, v58, v128
	v_add_f32_e32 v124, v59, v124
	v_add_f32_e32 v124, v60, v124
	v_add_f32_e32 v124, v61, v124
	v_cvt_pk_bf16_f32 v142, v56, v57
	v_cvt_pk_bf16_f32 v143, v58, v59
	ds_read_b64_tr_b16 v[56:57], v195 offset:27648
	ds_read_b64_tr_b16 v[58:59], v195 offset:28160
	v_mfma_f32_32x32x16_bf16 v[100:115], v[120:123], v[136:139], v[100:115]
	v_add_f32_e32 v120, v62, v124
	v_add_f32_e32 v120, v63, v120
	v_add_f32_e32 v120, v64, v120
	v_add_f32_e32 v120, v65, v120
	v_cvt_pk_bf16_f32 v132, v60, v61
	v_cvt_pk_bf16_f32 v133, v62, v63
	ds_read_b64_tr_b16 v[60:61], v195 offset:31744
	ds_read_b64_tr_b16 v[62:63], v195 offset:32256
	v_mfma_f32_32x32x16_bf16 v[84:99], v[116:119], v[136:139], v[84:99]
	v_add_f32_e32 v116, v66, v120
	v_add_f32_e32 v195, v67, v116
	v_cvt_pk_bf16_f32 v134, v64, v65
	v_cvt_pk_bf16_f32 v135, v66, v67
	s_add_i32 m0, s25, s59
	v_lshl_add_u64 v[64:65], v[0:1], 0, s[76:77]
	global_load_lds_dwordx4 v[64:65], off
	s_add_i32 m0, s44, s58
	v_lshl_add_u64 v[64:65], v[184:185], 0, s[34:35]
	global_load_lds_dwordx4 v[64:65], off
	s_waitcnt lgkmcnt(14)
	v_mfma_f32_32x32x16_bf16 v[4:19], v[152:155], v[196:199], v[4:19]
	v_exp_f32_e32 v100, v100
	v_exp_f32_e32 v101, v101
	v_exp_f32_e32 v102, v102
	v_exp_f32_e32 v103, v103
	s_waitcnt lgkmcnt(12)
	v_mfma_f32_32x32x16_bf16 v[20:35], v[152:155], v[68:71], v[20:35]
	v_exp_f32_e32 v104, v104
	v_exp_f32_e32 v105, v105
	v_exp_f32_e32 v106, v106
	v_exp_f32_e32 v107, v107
	v_add_u32_e32 v68, s44, v191
	ds_read_b128 v[64:67], v68
	ds_read_b128 v[120:123], v68 offset:512
	s_waitcnt lgkmcnt(12)
	v_mfma_f32_32x32x16_bf16 v[4:19], v[148:151], v[72:75], v[4:19]
	v_exp_f32_e32 v108, v108
	v_exp_f32_e32 v109, v109
	v_exp_f32_e32 v110, v110
	v_exp_f32_e32 v111, v111
	ds_read_b128 v[124:127], v68 offset:2048
	ds_read_b128 v[128:131], v68 offset:2560
	s_waitcnt lgkmcnt(12)
	v_mfma_f32_32x32x16_bf16 v[20:35], v[148:151], v[76:79], v[20:35]
	v_exp_f32_e32 v112, v112
	v_exp_f32_e32 v113, v113
	v_exp_f32_e32 v114, v114
	v_exp_f32_e32 v115, v115
	ds_read_b128 v[164:167], v68 offset:4096
	ds_read_b128 v[168:171], v68 offset:4608
	s_waitcnt lgkmcnt(12)
	v_mfma_f32_32x32x16_bf16 v[4:19], v[140:143], v[80:83], v[4:19]
	v_exp_f32_e32 v84, v84
	v_exp_f32_e32 v85, v85
	v_exp_f32_e32 v86, v86
	v_exp_f32_e32 v87, v87
	ds_read_b128 v[172:175], v68 offset:6144
	ds_read_b128 v[116:119], v68 offset:6656
	s_waitcnt lgkmcnt(12)
	v_mfma_f32_32x32x16_bf16 v[20:35], v[140:143], v[52:55], v[20:35]
	v_exp_f32_e32 v88, v88
	v_exp_f32_e32 v89, v89
	v_exp_f32_e32 v90, v90
	v_exp_f32_e32 v91, v91
	s_waitcnt lgkmcnt(10)
	v_mfma_f32_32x32x16_bf16 v[4:19], v[132:135], v[56:59], v[4:19]
	v_exp_f32_e32 v92, v92
	v_exp_f32_e32 v93, v93
	v_exp_f32_e32 v94, v94
	v_exp_f32_e32 v95, v95
	s_waitcnt lgkmcnt(8)
	v_mfma_f32_32x32x16_bf16 v[20:35], v[132:135], v[60:63], v[20:35]
	v_exp_f32_e32 v96, v96
	v_exp_f32_e32 v97, v97
	v_exp_f32_e32 v98, v98
	v_exp_f32_e32 v99, v99
	s_waitcnt vmcnt(2) lgkmcnt(0)
	s_barrier
	s_add_i32 s25, s44, 0x2000
	s_cmpk_lg_i32 s44, 0x4000
	s_cselect_b32 s25, s25, 0
	v_add_u32_e32 v200, s28, v190
	ds_read_b64_tr_b16 v[196:197], v200 offset:24576
	ds_read_b64_tr_b16 v[198:199], v200 offset:25088
	v_mfma_f32_32x32x16_bf16 v[68:83], v[64:67], v[160:163], 0
	v_add_f32_e32 v52, v100, v101
	v_add_f32_e32 v52, v102, v52
	v_add_f32_e32 v52, v103, v52
	v_add_f32_e32 v52, v104, v52
	v_add_f32_e32 v52, v105, v52
	v_cvt_pk_bf16_f32 v152, v100, v101
	v_cvt_pk_bf16_f32 v153, v102, v103
	ds_read_b64_tr_b16 v[100:101], v200 offset:28672
	ds_read_b64_tr_b16 v[102:103], v200 offset:29184
	v_add_f32_e32 v52, v106, v52
	v_add_f32_e32 v52, v107, v52
	v_add_f32_e32 v52, v108, v52
	v_add_f32_e32 v132, v109, v52
	v_mfma_f32_32x32x16_bf16 v[52:67], v[120:123], v[160:163], 0
	v_cvt_pk_bf16_f32 v154, v104, v105
	v_cvt_pk_bf16_f32 v155, v106, v107
	ds_read_b64_tr_b16 v[104:105], v200 offset:25600
	ds_read_b64_tr_b16 v[106:107], v200 offset:26112
	v_mfma_f32_32x32x16_bf16 v[68:83], v[124:127], v[156:159], v[68:83]
	v_add_f32_e32 v120, v110, v132
	v_add_f32_e32 v120, v111, v120
	v_add_f32_e32 v120, v112, v120
	v_add_f32_e32 v120, v113, v120
	v_cvt_pk_bf16_f32 v148, v108, v109
	v_cvt_pk_bf16_f32 v149, v110, v111
	ds_read_b64_tr_b16 v[108:109], v200 offset:29696
	ds_read_b64_tr_b16 v[110:111], v200 offset:30208
	v_mfma_f32_32x32x16_bf16 v[52:67], v[128:131], v[156:159], v[52:67]
	v_add_f32_e32 v120, v114, v120
	v_add_f32_e32 v120, v115, v120
	v_add_f32_e32 v120, v84, v120
	v_add_f32_e32 v120, v85, v120
	v_cvt_pk_bf16_f32 v150, v112, v113
	v_cvt_pk_bf16_f32 v151, v114, v115
	ds_read_b64_tr_b16 v[112:113], v200 offset:26624
	ds_read_b64_tr_b16 v[114:115], v200 offset:27136
	v_mfma_f32_32x32x16_bf16 v[68:83], v[164:167], v[144:147], v[68:83]
	v_add_f32_e32 v120, v86, v120
	v_add_f32_e32 v120, v87, v120
	v_add_f32_e32 v120, v88, v120
	v_add_f32_e32 v120, v89, v120
	v_cvt_pk_bf16_f32 v140, v84, v85
	v_cvt_pk_bf16_f32 v141, v86, v87
	ds_read_b64_tr_b16 v[206:207], v200 offset:30720
	ds_read_b64_tr_b16 v[208:209], v200 offset:31232
	v_mfma_f32_32x32x16_bf16 v[52:67], v[168:171], v[144:147], v[52:67]
	v_add_f32_e32 v84, v90, v120
	v_add_f32_e32 v84, v91, v84
	v_add_f32_e32 v84, v92, v84
	v_add_f32_e32 v84, v93, v84
	v_cvt_pk_bf16_f32 v142, v88, v89
	v_cvt_pk_bf16_f32 v143, v90, v91
	ds_read_b64_tr_b16 v[88:89], v200 offset:27648
	ds_read_b64_tr_b16 v[90:91], v200 offset:28160
	v_mfma_f32_32x32x16_bf16 v[68:83], v[172:175], v[136:139], v[68:83]
	v_add_f32_e32 v84, v94, v84
	v_add_f32_e32 v84, v95, v84
	v_add_f32_e32 v84, v96, v84
	v_add_f32_e32 v84, v97, v84
	v_cvt_pk_bf16_f32 v132, v92, v93
	v_cvt_pk_bf16_f32 v133, v94, v95
	ds_read_b64_tr_b16 v[92:93], v200 offset:31744
	ds_read_b64_tr_b16 v[94:95], v200 offset:32256
	v_mfma_f32_32x32x16_bf16 v[52:67], v[116:119], v[136:139], v[52:67]
	v_add_f32_e32 v84, v98, v84
	v_add_f32_e32 v200, v99, v84
	v_cvt_pk_bf16_f32 v134, v96, v97
	v_cvt_pk_bf16_f32 v135, v98, v99
	s_mov_b64 s[28:29], 0x10000
	s_add_i32 m0, s44, s59
	v_lshl_add_u64 v[84:85], v[0:1], 0, s[28:29]
	global_load_lds_dwordx4 v[84:85], off
	s_add_i32 m0, s25, s58
	v_lshl_add_u64 v[184:185], v[184:185], 0, s[36:37]
	global_load_lds_dwordx4 v[184:185], off
	s_waitcnt lgkmcnt(14)
	v_mfma_f32_32x32x16_bf16 v[4:19], v[152:155], v[196:199], v[4:19]
	v_exp_f32_e32 v68, v68
	v_exp_f32_e32 v69, v69
	v_exp_f32_e32 v70, v70
	v_exp_f32_e32 v71, v71
	s_waitcnt lgkmcnt(12)
	v_mfma_f32_32x32x16_bf16 v[20:35], v[152:155], v[100:103], v[20:35]
	v_exp_f32_e32 v72, v72
	v_exp_f32_e32 v73, v73
	v_exp_f32_e32 v74, v74
	v_exp_f32_e32 v75, v75
	v_add_u32_e32 v96, s25, v191
	ds_read_b128 v[84:87], v96
	ds_read_b128 v[168:171], v96 offset:512
	s_waitcnt lgkmcnt(12)
	v_mfma_f32_32x32x16_bf16 v[4:19], v[148:151], v[104:107], v[4:19]
	v_exp_f32_e32 v76, v76
	v_exp_f32_e32 v77, v77
	v_exp_f32_e32 v78, v78
	v_exp_f32_e32 v79, v79
	ds_read_b128 v[172:175], v96 offset:2048
	ds_read_b128 v[164:167], v96 offset:2560
	s_waitcnt lgkmcnt(12)
	v_mfma_f32_32x32x16_bf16 v[20:35], v[148:151], v[108:111], v[20:35]
	v_exp_f32_e32 v80, v80
	v_exp_f32_e32 v81, v81
	v_exp_f32_e32 v82, v82
	v_exp_f32_e32 v83, v83
	ds_read_b128 v[128:131], v96 offset:4096
	ds_read_b128 v[124:127], v96 offset:4608
	s_waitcnt lgkmcnt(12)
	v_mfma_f32_32x32x16_bf16 v[4:19], v[140:143], v[112:115], v[4:19]
	v_exp_f32_e32 v52, v52
	v_exp_f32_e32 v53, v53
	v_exp_f32_e32 v54, v54
	v_exp_f32_e32 v55, v55
	ds_read_b128 v[120:123], v96 offset:6144
	ds_read_b128 v[116:119], v96 offset:6656
	s_waitcnt lgkmcnt(12)
	v_mfma_f32_32x32x16_bf16 v[20:35], v[140:143], v[206:209], v[20:35]
	v_exp_f32_e32 v56, v56
	v_exp_f32_e32 v57, v57
	v_exp_f32_e32 v58, v58
	v_exp_f32_e32 v59, v59
	s_waitcnt lgkmcnt(10)
	v_mfma_f32_32x32x16_bf16 v[4:19], v[132:135], v[88:91], v[4:19]
	v_exp_f32_e32 v60, v60
	v_exp_f32_e32 v61, v61
	v_exp_f32_e32 v62, v62
	v_exp_f32_e32 v63, v63
	s_waitcnt lgkmcnt(8)
	v_mfma_f32_32x32x16_bf16 v[20:35], v[132:135], v[92:95], v[20:35]
	v_exp_f32_e32 v64, v64
	v_exp_f32_e32 v65, v65
	v_exp_f32_e32 v66, v66
	v_exp_f32_e32 v67, v67
	s_add_i32 s28, s25, 0x2000
	s_waitcnt vmcnt(2) lgkmcnt(0)
	s_barrier
	s_cmpk_lg_i32 s25, 0x4000
	v_add_f32_e32 v88, v192, v195
	s_cselect_b32 s29, s28, 0
	s_add_i32 s24, s24, 2
	v_add_f32_e32 v192, v88, v200
	v_lshl_add_u64 v[0:1], v[0:1], 0, s[36:37]
	s_cmpk_gt_u32 s24, 0xf8
	s_mov_b32 s45, s44
	s_cbranch_scc0 .LBB0_731
	s_and_b32 s24, s60, 0x3fffffc0
	s_cmp_lg_u32 0, -1
	s_cselect_b32 s28, 0, 0
	s_addk_i32 s28, 0x6000
	s_lshl_b32 s24, s24, 2
	v_add3_u32 v0, v194, s28, v193
	s_add_i32 s28, s24, 0
	v_add_u32_e32 v1, s44, v190
	ds_read_b64_tr_b16 v[194:195], v1 offset:24576
	ds_read_b64_tr_b16 v[196:197], v1 offset:25088
	v_add_f32_e32 v88, v68, v69
	v_add_f32_e32 v88, v70, v88
	v_add_f32_e32 v88, v71, v88
	v_add_f32_e32 v88, v72, v88
	v_add_f32_e32 v88, v73, v88
	v_cvt_pk_bf16_f32 v152, v68, v69
	v_cvt_pk_bf16_f32 v153, v70, v71
	s_waitcnt lgkmcnt(9)
	v_mfma_f32_32x32x16_bf16 v[100:115], v[84:87], v[160:163], v[36:51]
	ds_read_b64_tr_b16 v[68:69], v1 offset:28672
	ds_read_b64_tr_b16 v[70:71], v1 offset:29184
	v_add_f32_e32 v84, v74, v88
	v_add_f32_e32 v84, v75, v84
	v_add_f32_e32 v84, v76, v84
	v_add_f32_e32 v132, v77, v84
	v_cvt_pk_bf16_f32 v154, v72, v73
	v_cvt_pk_bf16_f32 v155, v74, v75
	s_waitcnt lgkmcnt(10)
	v_mfma_f32_32x32x16_bf16 v[84:99], v[168:171], v[160:163], v[36:51]
	ds_read_b64_tr_b16 v[72:73], v1 offset:25600
	ds_read_b64_tr_b16 v[74:75], v1 offset:26112
	v_add_f32_e32 v132, v78, v132
	v_add_f32_e32 v132, v79, v132
	v_add_f32_e32 v132, v80, v132
	v_add_f32_e32 v132, v81, v132
	v_cvt_pk_bf16_f32 v148, v76, v77
	v_cvt_pk_bf16_f32 v149, v78, v79
	s_waitcnt lgkmcnt(11)
	v_mfma_f32_32x32x16_bf16 v[100:115], v[172:175], v[156:159], v[100:115]
	ds_read_b64_tr_b16 v[76:77], v1 offset:29696
	ds_read_b64_tr_b16 v[78:79], v1 offset:30208
	v_add_f32_e32 v132, v82, v132
	v_add_f32_e32 v132, v83, v132
	v_add_f32_e32 v132, v52, v132
	v_add_f32_e32 v132, v53, v132
	v_cvt_pk_bf16_f32 v150, v80, v81
	v_cvt_pk_bf16_f32 v151, v82, v83
	s_waitcnt lgkmcnt(12)
	v_mfma_f32_32x32x16_bf16 v[84:99], v[164:167], v[156:159], v[84:99]
	ds_read_b64_tr_b16 v[80:81], v1 offset:26624
	ds_read_b64_tr_b16 v[82:83], v1 offset:27136
	s_waitcnt lgkmcnt(13)
	v_mfma_f32_32x32x16_bf16 v[100:115], v[128:131], v[144:147], v[100:115]
	v_add_f32_e32 v128, v54, v132
	v_add_f32_e32 v128, v55, v128
	v_add_f32_e32 v128, v56, v128
	v_add_f32_e32 v128, v57, v128
	v_cvt_pk_bf16_f32 v140, v52, v53
	v_cvt_pk_bf16_f32 v141, v54, v55
	ds_read_b64_tr_b16 v[52:53], v1 offset:30720
	ds_read_b64_tr_b16 v[54:55], v1 offset:31232
	s_waitcnt lgkmcnt(14)
	v_mfma_f32_32x32x16_bf16 v[84:99], v[124:127], v[144:147], v[84:99]
	v_add_f32_e32 v124, v58, v128
	v_add_f32_e32 v124, v59, v124
	v_add_f32_e32 v124, v60, v124
	v_add_f32_e32 v124, v61, v124
	v_cvt_pk_bf16_f32 v142, v56, v57
	v_cvt_pk_bf16_f32 v143, v58, v59
	ds_read_b64_tr_b16 v[56:57], v1 offset:27648
	ds_read_b64_tr_b16 v[58:59], v1 offset:28160
	s_waitcnt lgkmcnt(14)
	v_mfma_f32_32x32x16_bf16 v[100:115], v[120:123], v[136:139], v[100:115]
	v_add_f32_e32 v120, v62, v124
	v_add_f32_e32 v120, v63, v120
	v_add_f32_e32 v120, v64, v120
	v_add_f32_e32 v120, v65, v120
	v_cvt_pk_bf16_f32 v132, v60, v61
	v_cvt_pk_bf16_f32 v133, v62, v63
	ds_read_b64_tr_b16 v[60:61], v1 offset:31744
	ds_read_b64_tr_b16 v[62:63], v1 offset:32256
	v_add_f32_e32 v1, v66, v120
	v_add_f32_e32 v1, v67, v1
	v_add_f32_e32 v1, 0, v1
	v_cvt_pk_bf16_f32 v134, v64, v65
	v_cvt_pk_bf16_f32 v135, v66, v67
	v_mfma_f32_32x32x16_bf16 v[84:99], v[116:119], v[136:139], v[84:99]
	s_mov_b64 s[46:47], 0x3f8000
	s_add_i32 s24, s25, s59
	v_lshl_add_u64 v[64:65], v[182:183], 0, s[46:47]
	s_mov_b32 s44, m0
	s_mov_b32 m0, s24
	s_nop 0
	global_load_lds_dwordx4 v[64:65], off
	s_mov_b32 m0, s44
	s_mov_b64 s[44:45], 0x3f0000
	v_lshl_add_u64 v[64:65], v[180:181], 0, s[44:45]
	s_add_i32 s24, s29, s58
	s_mov_b32 s44, m0
	s_mov_b32 m0, s24
	s_nop 0
	global_load_lds_dwordx4 v[64:65], off
	s_mov_b32 m0, s44
	v_add_f32_e32 v1, v192, v1
	s_waitcnt lgkmcnt(14)
	v_mfma_f32_32x32x16_bf16 v[4:19], v[152:155], v[194:197], v[4:19]
	v_exp_f32_e32 v100, v100
	v_exp_f32_e32 v101, v101
	v_exp_f32_e32 v102, v102
	v_exp_f32_e32 v103, v103
	s_waitcnt lgkmcnt(12)
	v_mfma_f32_32x32x16_bf16 v[20:35], v[152:155], v[68:71], v[20:35]
	v_exp_f32_e32 v104, v104
	v_exp_f32_e32 v105, v105
	v_exp_f32_e32 v106, v106
	v_exp_f32_e32 v107, v107
	v_add_u32_e32 v68, s29, v191
	ds_read_b128 v[64:67], v68
	ds_read_b128 v[164:167], v68 offset:512
	s_waitcnt lgkmcnt(12)
	v_mfma_f32_32x32x16_bf16 v[4:19], v[148:151], v[72:75], v[4:19]
	v_exp_f32_e32 v108, v108
	v_exp_f32_e32 v109, v109
	v_exp_f32_e32 v110, v110
	v_exp_f32_e32 v111, v111
	ds_read_b128 v[72:75], v68 offset:2048
	ds_read_b128 v[168:171], v68 offset:2560
	s_waitcnt lgkmcnt(12)
	v_mfma_f32_32x32x16_bf16 v[20:35], v[148:151], v[76:79], v[20:35]
	v_exp_f32_e32 v112, v112
	v_exp_f32_e32 v113, v113
	v_exp_f32_e32 v114, v114
	v_exp_f32_e32 v115, v115
	ds_read_b128 v[76:79], v68 offset:4096
	ds_read_b128 v[172:175], v68 offset:4608
	s_waitcnt lgkmcnt(12)
	v_mfma_f32_32x32x16_bf16 v[4:19], v[140:143], v[80:83], v[4:19]
	v_exp_f32_e32 v84, v84
	v_exp_f32_e32 v85, v85
	v_exp_f32_e32 v86, v86
	v_exp_f32_e32 v87, v87
	ds_read_b128 v[80:83], v68 offset:6144
	ds_read_b128 v[68:71], v68 offset:6656
	s_waitcnt lgkmcnt(12)
	v_mfma_f32_32x32x16_bf16 v[20:35], v[140:143], v[52:55], v[20:35]
	v_exp_f32_e32 v88, v88
	v_exp_f32_e32 v89, v89
	v_exp_f32_e32 v90, v90
	v_exp_f32_e32 v91, v91
	s_waitcnt lgkmcnt(10)
	v_mfma_f32_32x32x16_bf16 v[4:19], v[132:135], v[56:59], v[4:19]
	v_exp_f32_e32 v92, v92
	v_exp_f32_e32 v93, v93
	v_exp_f32_e32 v94, v94
	v_exp_f32_e32 v95, v95
	s_waitcnt lgkmcnt(8)
	v_mfma_f32_32x32x16_bf16 v[20:35], v[132:135], v[60:63], v[20:35]
	v_exp_f32_e32 v96, v96
	v_exp_f32_e32 v97, v97
	v_exp_f32_e32 v98, v98
	v_exp_f32_e32 v99, v99
	s_waitcnt vmcnt(2) lgkmcnt(0)
	s_barrier
	s_add_i32 s24, s29, 0x2000
	s_cmpk_lg_i32 s29, 0x4000
	s_cselect_b32 s44, s24, 0
	v_add_u32_e32 v184, s25, v190
	ds_read_b64_tr_b16 v[192:193], v184 offset:24576
	ds_read_b64_tr_b16 v[194:195], v184 offset:25088
	v_add_f32_e32 v52, v100, v101
	v_add_f32_e32 v52, v102, v52
	v_add_f32_e32 v52, v103, v52
	v_add_f32_e32 v52, v104, v52
	v_add_f32_e32 v52, v105, v52
	v_cvt_pk_bf16_f32 v152, v100, v101
	v_cvt_pk_bf16_f32 v153, v102, v103
	s_waitcnt lgkmcnt(9)
	v_mfma_f32_32x32x16_bf16 v[116:131], v[64:67], v[160:163], v[36:51]
	ds_read_b64_tr_b16 v[100:101], v184 offset:28672
	ds_read_b64_tr_b16 v[102:103], v184 offset:29184
	v_add_f32_e32 v52, v106, v52
	v_add_f32_e32 v52, v107, v52
	v_add_f32_e32 v52, v108, v52
	v_add_f32_e32 v132, v109, v52
	v_cvt_pk_bf16_f32 v154, v104, v105
	v_cvt_pk_bf16_f32 v155, v106, v107
	s_waitcnt lgkmcnt(10)
	v_mfma_f32_32x32x16_bf16 v[52:67], v[164:167], v[160:163], v[36:51]
	ds_read_b64_tr_b16 v[104:105], v184 offset:25600
	ds_read_b64_tr_b16 v[106:107], v184 offset:26112
	s_waitcnt lgkmcnt(11)
	v_mfma_f32_32x32x16_bf16 v[116:131], v[72:75], v[156:159], v[116:131]
	v_add_f32_e32 v72, v110, v132
	v_add_f32_e32 v72, v111, v72
	v_add_f32_e32 v72, v112, v72
	v_add_f32_e32 v132, v113, v72
	v_cvt_pk_bf16_f32 v148, v108, v109
	v_cvt_pk_bf16_f32 v149, v110, v111
	ds_read_b64_tr_b16 v[72:73], v184 offset:29696
	ds_read_b64_tr_b16 v[74:75], v184 offset:30208
	v_add_f32_e32 v108, v114, v132
	v_add_f32_e32 v108, v115, v108
	v_add_f32_e32 v108, v84, v108
	v_add_f32_e32 v132, v85, v108
	v_cvt_pk_bf16_f32 v150, v112, v113
	v_cvt_pk_bf16_f32 v151, v114, v115
	s_waitcnt lgkmcnt(12)
	v_mfma_f32_32x32x16_bf16 v[52:67], v[168:171], v[156:159], v[52:67]
	ds_read_b64_tr_b16 v[108:109], v184 offset:26624
	ds_read_b64_tr_b16 v[110:111], v184 offset:27136
	s_waitcnt lgkmcnt(13)
	v_mfma_f32_32x32x16_bf16 v[116:131], v[76:79], v[144:147], v[116:131]
	v_add_f32_e32 v76, v86, v132
	v_add_f32_e32 v76, v87, v76
	v_add_f32_e32 v76, v88, v76
	v_add_f32_e32 v112, v89, v76
	v_cvt_pk_bf16_f32 v140, v84, v85
	v_cvt_pk_bf16_f32 v141, v86, v87
	ds_read_b64_tr_b16 v[76:77], v184 offset:30720
	ds_read_b64_tr_b16 v[78:79], v184 offset:31232
	v_add_f32_e32 v84, v90, v112
	v_add_f32_e32 v84, v91, v84
	v_add_f32_e32 v84, v92, v84
	v_add_f32_e32 v84, v93, v84
	v_cvt_pk_bf16_f32 v142, v88, v89
	v_cvt_pk_bf16_f32 v143, v90, v91
	s_waitcnt lgkmcnt(14)
	v_mfma_f32_32x32x16_bf16 v[52:67], v[172:175], v[144:147], v[52:67]
	ds_read_b64_tr_b16 v[88:89], v184 offset:27648
	ds_read_b64_tr_b16 v[90:91], v184 offset:28160
	s_waitcnt lgkmcnt(14)
	v_mfma_f32_32x32x16_bf16 v[116:131], v[80:83], v[136:139], v[116:131]
	v_add_f32_e32 v80, v94, v84
	v_add_f32_e32 v80, v95, v80
	v_add_f32_e32 v80, v96, v80
	v_add_f32_e32 v84, v97, v80
	v_cvt_pk_bf16_f32 v132, v92, v93
	v_cvt_pk_bf16_f32 v133, v94, v95
	ds_read_b64_tr_b16 v[80:81], v184 offset:31744
	ds_read_b64_tr_b16 v[82:83], v184 offset:32256
	v_mfma_f32_32x32x16_bf16 v[52:67], v[68:71], v[136:139], v[52:67]
	v_add_f32_e32 v68, v98, v84
	v_add_f32_e32 v68, v99, v68
	v_add_f32_e32 v68, 0, v68
	v_cvt_pk_bf16_f32 v134, v96, v97
	v_cvt_pk_bf16_f32 v135, v98, v99
	s_mov_b64 s[60:61], 0x3fc000
	v_add_f32_e32 v1, v1, v68
	s_add_i32 s24, s29, s59
	v_lshl_add_u64 v[68:69], v[182:183], 0, s[60:61]
	s_mov_b32 s25, m0
	s_mov_b32 m0, s24
	s_nop 0
	global_load_lds_dwordx4 v[68:69], off
	s_mov_b32 m0, s25
	s_mov_b64 s[24:25], 0x3f4000
	s_add_i32 s45, s44, s58
	v_lshl_add_u64 v[68:69], v[180:181], 0, s[24:25]
	s_mov_b32 s24, m0
	s_mov_b32 m0, s45
	s_nop 0
	global_load_lds_dwordx4 v[68:69], off
	s_mov_b32 m0, s24
	s_waitcnt lgkmcnt(14)
	v_mfma_f32_32x32x16_bf16 v[4:19], v[152:155], v[192:195], v[4:19]
	v_exp_f32_e32 v116, v116
	v_exp_f32_e32 v117, v117
	v_exp_f32_e32 v118, v118
	v_exp_f32_e32 v119, v119
	s_waitcnt lgkmcnt(12)
	v_mfma_f32_32x32x16_bf16 v[20:35], v[152:155], v[100:103], v[20:35]
	v_exp_f32_e32 v120, v120
	v_exp_f32_e32 v121, v121
	v_exp_f32_e32 v122, v122
	v_exp_f32_e32 v123, v123
	v_add_u32_e32 v84, s44, v191
	ds_read_b128 v[68:71], v84
	ds_read_b128 v[92:95], v84 offset:512
	s_waitcnt lgkmcnt(12)
	v_mfma_f32_32x32x16_bf16 v[4:19], v[148:151], v[104:107], v[4:19]
	v_exp_f32_e32 v124, v124
	v_exp_f32_e32 v125, v125
	v_exp_f32_e32 v126, v126
	v_exp_f32_e32 v127, v127
	ds_read_b128 v[96:99], v84 offset:2048
	ds_read_b128 v[164:167], v84 offset:2560
	s_waitcnt lgkmcnt(12)
	v_mfma_f32_32x32x16_bf16 v[20:35], v[148:151], v[72:75], v[20:35]
	v_exp_f32_e32 v128, v128
	v_exp_f32_e32 v129, v129
	v_exp_f32_e32 v130, v130
	v_exp_f32_e32 v131, v131
	ds_read_b128 v[168:171], v84 offset:4096
	ds_read_b128 v[172:175], v84 offset:4608
	s_waitcnt lgkmcnt(12)
	v_mfma_f32_32x32x16_bf16 v[4:19], v[140:143], v[108:111], v[4:19]
	v_exp_f32_e32 v52, v52
	v_exp_f32_e32 v53, v53
	v_exp_f32_e32 v54, v54
	v_exp_f32_e32 v55, v55
	ds_read_b128 v[182:185], v84 offset:6144
	ds_read_b128 v[84:87], v84 offset:6656
	s_waitcnt lgkmcnt(12)
	v_mfma_f32_32x32x16_bf16 v[20:35], v[140:143], v[76:79], v[20:35]
	v_exp_f32_e32 v56, v56
	v_exp_f32_e32 v57, v57
	v_exp_f32_e32 v58, v58
	v_exp_f32_e32 v59, v59
	s_waitcnt lgkmcnt(10)
	v_mfma_f32_32x32x16_bf16 v[4:19], v[132:135], v[88:91], v[4:19]
	v_exp_f32_e32 v60, v60
	v_exp_f32_e32 v61, v61
	v_exp_f32_e32 v62, v62
	v_exp_f32_e32 v63, v63
	s_waitcnt lgkmcnt(8)
	v_mfma_f32_32x32x16_bf16 v[20:35], v[132:135], v[80:83], v[20:35]
	v_exp_f32_e32 v64, v64
	v_exp_f32_e32 v65, v65
	v_exp_f32_e32 v66, v66
	v_exp_f32_e32 v67, v67
	s_waitcnt vmcnt(2) lgkmcnt(0)
	s_barrier
	s_add_i32 s24, s44, 0x2000
	s_cmpk_lg_i32 s44, 0x4000
	s_cselect_b32 s25, s24, 0
	v_add_u32_e32 v192, s29, v190
	ds_read_b64_tr_b16 v[88:89], v192 offset:24576
	ds_read_b64_tr_b16 v[90:91], v192 offset:25088
	v_add_f32_e32 v72, v116, v117
	v_add_f32_e32 v72, v118, v72
	v_add_f32_e32 v72, v119, v72
	v_add_f32_e32 v72, v120, v72
	v_add_f32_e32 v72, v121, v72
	v_cvt_pk_bf16_f32 v152, v116, v117
	v_cvt_pk_bf16_f32 v153, v118, v119
	s_waitcnt lgkmcnt(9)
	v_mfma_f32_32x32x16_bf16 v[100:115], v[68:71], v[160:163], v[36:51]
	ds_read_b64_tr_b16 v[116:117], v192 offset:28672
	ds_read_b64_tr_b16 v[118:119], v192 offset:29184
	v_add_f32_e32 v68, v122, v72
	v_add_f32_e32 v68, v123, v68
	v_add_f32_e32 v68, v124, v68
	v_add_f32_e32 v132, v125, v68
	v_cvt_pk_bf16_f32 v154, v120, v121
	v_cvt_pk_bf16_f32 v155, v122, v123
	s_waitcnt lgkmcnt(10)
	v_mfma_f32_32x32x16_bf16 v[68:83], v[92:95], v[160:163], v[36:51]
	ds_read_b64_tr_b16 v[92:93], v192 offset:25600
	ds_read_b64_tr_b16 v[94:95], v192 offset:26112
	s_waitcnt lgkmcnt(11)
	v_mfma_f32_32x32x16_bf16 v[100:115], v[96:99], v[156:159], v[100:115]
	v_add_f32_e32 v96, v126, v132
	v_add_f32_e32 v96, v127, v96
	v_add_f32_e32 v96, v128, v96
	v_add_f32_e32 v120, v129, v96
	v_cvt_pk_bf16_f32 v148, v124, v125
	v_cvt_pk_bf16_f32 v149, v126, v127
	ds_read_b64_tr_b16 v[96:97], v192 offset:29696
	ds_read_b64_tr_b16 v[98:99], v192 offset:30208
	v_add_f32_e32 v120, v130, v120
	v_add_f32_e32 v120, v131, v120
	v_add_f32_e32 v120, v52, v120
	v_add_f32_e32 v124, v53, v120
	v_cvt_pk_bf16_f32 v150, v128, v129
	v_cvt_pk_bf16_f32 v151, v130, v131
	s_waitcnt lgkmcnt(12)
	v_mfma_f32_32x32x16_bf16 v[68:83], v[164:167], v[156:159], v[68:83]
	ds_read_b64_tr_b16 v[120:121], v192 offset:26624
	ds_read_b64_tr_b16 v[122:123], v192 offset:27136
	v_add_f32_e32 v124, v54, v124
	v_add_f32_e32 v124, v55, v124
	v_add_f32_e32 v124, v56, v124
	v_add_f32_e32 v124, v57, v124
	v_cvt_pk_bf16_f32 v140, v52, v53
	v_cvt_pk_bf16_f32 v141, v54, v55
	s_waitcnt lgkmcnt(13)
	v_mfma_f32_32x32x16_bf16 v[100:115], v[168:171], v[144:147], v[100:115]
	ds_read_b64_tr_b16 v[52:53], v192 offset:30720
	ds_read_b64_tr_b16 v[54:55], v192 offset:31232
	v_add_f32_e32 v124, v58, v124
	v_add_f32_e32 v124, v59, v124
	v_add_f32_e32 v124, v60, v124
	v_add_f32_e32 v124, v61, v124
	v_cvt_pk_bf16_f32 v142, v56, v57
	v_cvt_pk_bf16_f32 v143, v58, v59
	s_waitcnt lgkmcnt(14)
	v_mfma_f32_32x32x16_bf16 v[68:83], v[172:175], v[144:147], v[68:83]
	ds_read_b64_tr_b16 v[56:57], v192 offset:27648
	ds_read_b64_tr_b16 v[58:59], v192 offset:28160
	v_add_f32_e32 v124, v62, v124
	v_add_f32_e32 v124, v63, v124
	v_add_f32_e32 v124, v64, v124
	v_add_f32_e32 v124, v65, v124
	v_cvt_pk_bf16_f32 v132, v60, v61
	v_cvt_pk_bf16_f32 v133, v62, v63
	s_waitcnt lgkmcnt(14)
	v_mfma_f32_32x32x16_bf16 v[100:115], v[182:185], v[136:139], v[100:115]
	ds_read_b64_tr_b16 v[60:61], v192 offset:31744
	ds_read_b64_tr_b16 v[62:63], v192 offset:32256
	v_mfma_f32_32x32x16_bf16 v[68:83], v[84:87], v[136:139], v[68:83]
	v_add_f32_e32 v84, v66, v124
	v_add_f32_e32 v84, v67, v84
	v_add_f32_e32 v84, 0, v84
	v_cvt_pk_bf16_f32 v134, v64, v65
	v_cvt_pk_bf16_f32 v135, v66, v67
	v_lshl_add_u64 v[64:65], v[180:181], 0, s[46:47]
	s_add_i32 s24, s25, s58
	s_mov_b32 s29, m0
	s_mov_b32 m0, s24
	s_nop 0
	global_load_lds_dwordx4 v[64:65], off
	s_mov_b32 m0, s29
	v_add_f32_e32 v1, v1, v84
	s_waitcnt lgkmcnt(14)
	v_mfma_f32_32x32x16_bf16 v[4:19], v[152:155], v[88:91], v[4:19]
	v_exp_f32_e32 v100, v100
	v_exp_f32_e32 v101, v101
	v_exp_f32_e32 v102, v102
	v_exp_f32_e32 v103, v103
	s_waitcnt lgkmcnt(12)
	v_mfma_f32_32x32x16_bf16 v[20:35], v[152:155], v[116:119], v[20:35]
	v_exp_f32_e32 v104, v104
	v_exp_f32_e32 v105, v105
	v_exp_f32_e32 v106, v106
	v_exp_f32_e32 v107, v107
	v_add_u32_e32 v84, s25, v191
	ds_read_b128 v[64:67], v84
	ds_read_b128 v[124:127], v84 offset:512
	s_waitcnt lgkmcnt(12)
	v_mfma_f32_32x32x16_bf16 v[4:19], v[148:151], v[92:95], v[4:19]
	v_exp_f32_e32 v108, v108
	v_exp_f32_e32 v109, v109
	v_exp_f32_e32 v110, v110
	v_exp_f32_e32 v111, v111
	ds_read_b128 v[128:131], v84 offset:2048
	ds_read_b128 v[164:167], v84 offset:2560
	s_waitcnt lgkmcnt(12)
	v_mfma_f32_32x32x16_bf16 v[20:35], v[148:151], v[96:99], v[20:35]
	v_exp_f32_e32 v112, v112
	v_exp_f32_e32 v113, v113
	v_exp_f32_e32 v114, v114
	v_exp_f32_e32 v115, v115
	ds_read_b128 v[168:171], v84 offset:4096
	ds_read_b128 v[172:175], v84 offset:4608
	s_waitcnt lgkmcnt(12)
	v_mfma_f32_32x32x16_bf16 v[4:19], v[140:143], v[120:123], v[4:19]
	v_exp_f32_e32 v68, v68
	v_exp_f32_e32 v69, v69
	v_exp_f32_e32 v70, v70
	v_exp_f32_e32 v71, v71
	ds_read_b128 v[120:123], v84 offset:6144
	ds_read_b128 v[116:119], v84 offset:6656
	s_waitcnt lgkmcnt(12)
	v_mfma_f32_32x32x16_bf16 v[20:35], v[140:143], v[52:55], v[20:35]
	v_exp_f32_e32 v72, v72
	v_exp_f32_e32 v73, v73
	v_exp_f32_e32 v74, v74
	v_exp_f32_e32 v75, v75
	s_waitcnt lgkmcnt(10)
	v_mfma_f32_32x32x16_bf16 v[4:19], v[132:135], v[56:59], v[4:19]
	v_exp_f32_e32 v76, v76
	v_exp_f32_e32 v77, v77
	v_exp_f32_e32 v78, v78
	v_exp_f32_e32 v79, v79
	s_waitcnt lgkmcnt(8)
	v_mfma_f32_32x32x16_bf16 v[20:35], v[132:135], v[60:63], v[20:35]
	v_exp_f32_e32 v80, v80
	v_exp_f32_e32 v81, v81
	v_exp_f32_e32 v82, v82
	v_exp_f32_e32 v83, v83
	s_waitcnt vmcnt(1) lgkmcnt(0)
	s_barrier
	s_add_i32 s24, s25, 0x2000
	s_cmpk_lg_i32 s25, 0x4000
	s_cselect_b32 s24, s24, 0
	v_add_u32_e32 v192, s44, v190
	ds_read_b64_tr_b16 v[182:183], v192 offset:24576
	ds_read_b64_tr_b16 v[184:185], v192 offset:25088
	v_add_f32_e32 v52, v100, v101
	v_add_f32_e32 v52, v102, v52
	v_add_f32_e32 v52, v103, v52
	v_add_f32_e32 v52, v104, v52
	v_add_f32_e32 v52, v105, v52
	v_cvt_pk_bf16_f32 v152, v100, v101
	v_cvt_pk_bf16_f32 v153, v102, v103
	s_waitcnt lgkmcnt(9)
	v_mfma_f32_32x32x16_bf16 v[84:99], v[64:67], v[160:163], v[36:51]
	ds_read_b64_tr_b16 v[100:101], v192 offset:28672
	ds_read_b64_tr_b16 v[102:103], v192 offset:29184
	v_add_f32_e32 v52, v106, v52
	v_add_f32_e32 v52, v107, v52
	v_add_f32_e32 v52, v108, v52
	v_add_f32_e32 v132, v109, v52
	v_cvt_pk_bf16_f32 v154, v104, v105
	v_cvt_pk_bf16_f32 v155, v106, v107
	s_waitcnt lgkmcnt(10)
	v_mfma_f32_32x32x16_bf16 v[52:67], v[124:127], v[160:163], v[36:51]
	ds_read_b64_tr_b16 v[104:105], v192 offset:25600
	ds_read_b64_tr_b16 v[106:107], v192 offset:26112
	v_add_f32_e32 v124, v110, v132
	v_add_f32_e32 v124, v111, v124
	v_add_f32_e32 v124, v112, v124
	v_add_f32_e32 v124, v113, v124
	v_cvt_pk_bf16_f32 v148, v108, v109
	v_cvt_pk_bf16_f32 v149, v110, v111
	s_waitcnt lgkmcnt(11)
	v_mfma_f32_32x32x16_bf16 v[84:99], v[128:131], v[156:159], v[84:99]
	ds_read_b64_tr_b16 v[108:109], v192 offset:29696
	ds_read_b64_tr_b16 v[110:111], v192 offset:30208
	v_add_f32_e32 v124, v114, v124
	v_add_f32_e32 v124, v115, v124
	v_add_f32_e32 v124, v68, v124
	v_add_f32_e32 v124, v69, v124
	v_cvt_pk_bf16_f32 v150, v112, v113
	v_cvt_pk_bf16_f32 v151, v114, v115
	s_waitcnt lgkmcnt(12)
	v_mfma_f32_32x32x16_bf16 v[52:67], v[164:167], v[156:159], v[52:67]
	ds_read_b64_tr_b16 v[112:113], v192 offset:26624
	ds_read_b64_tr_b16 v[114:115], v192 offset:27136
	v_add_f32_e32 v124, v70, v124
	v_add_f32_e32 v124, v71, v124
	v_add_f32_e32 v124, v72, v124
	v_add_f32_e32 v124, v73, v124
	v_cvt_pk_bf16_f32 v140, v68, v69
	v_cvt_pk_bf16_f32 v141, v70, v71
	s_waitcnt lgkmcnt(13)
	v_mfma_f32_32x32x16_bf16 v[84:99], v[168:171], v[144:147], v[84:99]
	ds_read_b64_tr_b16 v[68:69], v192 offset:30720
	ds_read_b64_tr_b16 v[70:71], v192 offset:31232
	v_add_f32_e32 v124, v74, v124
	v_add_f32_e32 v124, v75, v124
	v_add_f32_e32 v124, v76, v124
	v_add_f32_e32 v124, v77, v124
	v_cvt_pk_bf16_f32 v142, v72, v73
	v_cvt_pk_bf16_f32 v143, v74, v75
	s_waitcnt lgkmcnt(14)
	v_mfma_f32_32x32x16_bf16 v[52:67], v[172:175], v[144:147], v[52:67]
	ds_read_b64_tr_b16 v[72:73], v192 offset:27648
	ds_read_b64_tr_b16 v[74:75], v192 offset:28160
	s_waitcnt lgkmcnt(14)
	v_mfma_f32_32x32x16_bf16 v[84:99], v[120:123], v[136:139], v[84:99]
	v_add_f32_e32 v120, v78, v124
	v_add_f32_e32 v120, v79, v120
	v_add_f32_e32 v120, v80, v120
	v_add_f32_e32 v120, v81, v120
	v_cvt_pk_bf16_f32 v132, v76, v77
	v_cvt_pk_bf16_f32 v133, v78, v79
	ds_read_b64_tr_b16 v[76:77], v192 offset:31744
	ds_read_b64_tr_b16 v[78:79], v192 offset:32256
	v_mfma_f32_32x32x16_bf16 v[52:67], v[116:119], v[136:139], v[52:67]
	v_add_f32_e32 v116, v82, v120
	v_add_f32_e32 v116, v83, v116
	v_add_f32_e32 v116, 0, v116
	v_cvt_pk_bf16_f32 v134, v80, v81
	v_cvt_pk_bf16_f32 v135, v82, v83
	s_add_i32 s29, s24, s58
	v_lshl_add_u64 v[80:81], v[180:181], 0, s[60:61]
	s_mov_b32 s44, m0
	s_mov_b32 m0, s29
	s_nop 0
	global_load_lds_dwordx4 v[80:81], off
	s_mov_b32 m0, s44
	v_add_f32_e32 v1, v1, v116
	s_waitcnt lgkmcnt(14)
	v_mfma_f32_32x32x16_bf16 v[4:19], v[152:155], v[182:185], v[4:19]
	v_exp_f32_e32 v84, v84
	v_exp_f32_e32 v85, v85
	v_exp_f32_e32 v86, v86
	v_exp_f32_e32 v87, v87
	s_waitcnt lgkmcnt(12)
	v_mfma_f32_32x32x16_bf16 v[20:35], v[152:155], v[100:103], v[20:35]
	v_exp_f32_e32 v88, v88
	v_exp_f32_e32 v89, v89
	v_exp_f32_e32 v90, v90
	v_exp_f32_e32 v91, v91
	v_add_u32_e32 v80, s24, v191
	ds_read_b128 v[116:119], v80
	ds_read_b128 v[120:123], v80 offset:512
	s_waitcnt lgkmcnt(12)
	v_mfma_f32_32x32x16_bf16 v[4:19], v[148:151], v[104:107], v[4:19]
	v_exp_f32_e32 v92, v92
	v_exp_f32_e32 v93, v93
	v_exp_f32_e32 v94, v94
	v_exp_f32_e32 v95, v95
	ds_read_b128 v[104:107], v80 offset:2048
	ds_read_b128 v[124:127], v80 offset:2560
	s_waitcnt lgkmcnt(12)
	v_mfma_f32_32x32x16_bf16 v[20:35], v[148:151], v[108:111], v[20:35]
	v_exp_f32_e32 v96, v96
	v_exp_f32_e32 v97, v97
	v_exp_f32_e32 v98, v98
	v_exp_f32_e32 v99, v99
	ds_read_b128 v[108:111], v80 offset:4096
	ds_read_b128 v[128:131], v80 offset:4608
	s_waitcnt lgkmcnt(12)
	v_mfma_f32_32x32x16_bf16 v[4:19], v[140:143], v[112:115], v[4:19]
	v_exp_f32_e32 v52, v52
	v_exp_f32_e32 v53, v53
	v_exp_f32_e32 v54, v54
	v_exp_f32_e32 v55, v55
	ds_read_b128 v[112:115], v80 offset:6144
	ds_read_b128 v[100:103], v80 offset:6656
	s_waitcnt lgkmcnt(12)
	v_mfma_f32_32x32x16_bf16 v[20:35], v[140:143], v[68:71], v[20:35]
	v_exp_f32_e32 v56, v56
	v_exp_f32_e32 v57, v57
	v_exp_f32_e32 v58, v58
	v_exp_f32_e32 v59, v59
	s_waitcnt lgkmcnt(10)
	v_mfma_f32_32x32x16_bf16 v[4:19], v[132:135], v[72:75], v[4:19]
	v_exp_f32_e32 v60, v60
	v_exp_f32_e32 v61, v61
	v_exp_f32_e32 v62, v62
	v_exp_f32_e32 v63, v63
	s_waitcnt lgkmcnt(8)
	v_mfma_f32_32x32x16_bf16 v[20:35], v[132:135], v[76:79], v[20:35]
	v_exp_f32_e32 v64, v64
	v_exp_f32_e32 v65, v65
	v_exp_f32_e32 v66, v66
	v_exp_f32_e32 v67, v67
	s_waitcnt vmcnt(0) lgkmcnt(0)
	s_barrier
	v_and_b32_e32 v245, 63, v201
	v_lshrrev_b32_e32 v246, 6, v201
	v_and_b32_e32 v248, 3, v246
	v_lshl_add_u32 v248, v248, 6, v245
	v_lshlrev_b32_e32 v248, 8, v248
	v_lshrrev_b32_e32 v249, 2, v246
	v_lshl_add_u32 v248, v249, 23, v248
	global_load_dword v250, v248, s[98:99]
	v_and_b32_e32 v251, 31, v245
	v_lshlrev_b32_e32 v251, 10, v251
	global_load_dword v252, v251, s[100:101]
	v_add_u32_e32 v168, s25, v190
	ds_read_b64_tr_b16 v[164:165], v168 offset:24576
	ds_read_b64_tr_b16 v[166:167], v168 offset:25088
	v_add_f32_e32 v68, v84, v85
	v_add_f32_e32 v68, v86, v68
	v_add_f32_e32 v68, v87, v68
	v_add_f32_e32 v68, v88, v68
	v_add_f32_e32 v132, v89, v68
	v_cvt_pk_bf16_f32 v152, v84, v85
	v_cvt_pk_bf16_f32 v153, v86, v87
	s_waitcnt lgkmcnt(9)
	v_mfma_f32_32x32x16_bf16 v[68:83], v[116:119], v[160:163], v[36:51]
	ds_read_b64_tr_b16 v[84:85], v168 offset:28672
	ds_read_b64_tr_b16 v[86:87], v168 offset:29184
	v_add_f32_e32 v116, v90, v132
	v_add_f32_e32 v116, v91, v116
	v_add_f32_e32 v116, v92, v116
	v_add_f32_e32 v116, v93, v116
	v_cvt_pk_bf16_f32 v154, v88, v89
	v_cvt_pk_bf16_f32 v155, v90, v91
	s_waitcnt lgkmcnt(10)
	v_mfma_f32_32x32x16_bf16 v[36:51], v[120:123], v[160:163], v[36:51]
	ds_read_b64_tr_b16 v[88:89], v168 offset:25600
	ds_read_b64_tr_b16 v[90:91], v168 offset:26112
	s_waitcnt lgkmcnt(11)
	v_mfma_f32_32x32x16_bf16 v[68:83], v[104:107], v[156:159], v[68:83]
	v_add_f32_e32 v104, v94, v116
	v_add_f32_e32 v104, v95, v104
	v_add_f32_e32 v104, v96, v104
	v_add_f32_e32 v104, v97, v104
	v_cvt_pk_bf16_f32 v148, v92, v93
	v_cvt_pk_bf16_f32 v149, v94, v95
	ds_read_b64_tr_b16 v[92:93], v168 offset:29696
	ds_read_b64_tr_b16 v[94:95], v168 offset:30208
	v_add_f32_e32 v104, v98, v104
	v_add_f32_e32 v104, v99, v104
	v_add_f32_e32 v104, v52, v104
	v_add_f32_e32 v104, v53, v104
	v_cvt_pk_bf16_f32 v150, v96, v97
	v_cvt_pk_bf16_f32 v151, v98, v99
	s_waitcnt lgkmcnt(12)
	v_mfma_f32_32x32x16_bf16 v[36:51], v[124:127], v[156:159], v[36:51]
	ds_read_b64_tr_b16 v[96:97], v168 offset:26624
	ds_read_b64_tr_b16 v[98:99], v168 offset:27136
	v_add_f32_e32 v104, v54, v104
	v_add_f32_e32 v104, v55, v104
	v_add_f32_e32 v104, v56, v104
	v_add_f32_e32 v104, v57, v104
	v_cvt_pk_bf16_f32 v140, v52, v53
	v_cvt_pk_bf16_f32 v141, v54, v55
	s_waitcnt lgkmcnt(13)
	v_mfma_f32_32x32x16_bf16 v[68:83], v[108:111], v[144:147], v[68:83]
	ds_read_b64_tr_b16 v[52:53], v168 offset:30720
	ds_read_b64_tr_b16 v[54:55], v168 offset:31232
	v_add_f32_e32 v104, v58, v104
	v_add_f32_e32 v104, v59, v104
	v_add_f32_e32 v104, v60, v104
	v_add_f32_e32 v104, v61, v104
	v_cvt_pk_bf16_f32 v142, v56, v57
	v_cvt_pk_bf16_f32 v143, v58, v59
	s_waitcnt lgkmcnt(14)
	v_mfma_f32_32x32x16_bf16 v[36:51], v[128:131], v[144:147], v[36:51]
	ds_read_b64_tr_b16 v[56:57], v168 offset:27648
	ds_read_b64_tr_b16 v[58:59], v168 offset:28160
	v_add_f32_e32 v104, v62, v104
	v_add_f32_e32 v104, v63, v104
	v_add_f32_e32 v104, v64, v104
	v_add_f32_e32 v104, v65, v104
	v_cvt_pk_bf16_f32 v132, v60, v61
	v_cvt_pk_bf16_f32 v133, v62, v63
	s_waitcnt lgkmcnt(14)
	v_mfma_f32_32x32x16_bf16 v[68:83], v[112:115], v[136:139], v[68:83]
	ds_read_b64_tr_b16 v[60:61], v168 offset:31744
	ds_read_b64_tr_b16 v[62:63], v168 offset:32256
	v_mfma_f32_32x32x16_bf16 v[36:51], v[100:103], v[136:139], v[36:51]
	v_add_f32_e32 v100, v66, v104
	v_add_f32_e32 v100, v67, v100
	v_add_f32_e32 v100, 0, v100
	v_cvt_pk_bf16_f32 v134, v64, v65
	v_cvt_pk_bf16_f32 v135, v66, v67
	s_waitcnt lgkmcnt(14)
	v_mfma_f32_32x32x16_bf16 v[4:19], v[152:155], v[164:167], v[4:19]
	s_nop 1
	v_exp_f32_e32 v68, v68
	v_exp_f32_e32 v69, v69
	v_exp_f32_e32 v70, v70
	v_exp_f32_e32 v71, v71
	s_waitcnt lgkmcnt(12)
	v_mfma_f32_32x32x16_bf16 v[20:35], v[152:155], v[84:87], v[20:35]
	v_exp_f32_e32 v72, v72
	v_exp_f32_e32 v73, v73
	v_exp_f32_e32 v74, v74
	v_exp_f32_e32 v75, v75
	s_waitcnt lgkmcnt(10)
	v_mfma_f32_32x32x16_bf16 v[4:19], v[148:151], v[88:91], v[4:19]
	v_exp_f32_e32 v76, v76
	v_exp_f32_e32 v77, v77
	v_exp_f32_e32 v78, v78
	v_exp_f32_e32 v79, v79
	s_waitcnt lgkmcnt(8)
	v_mfma_f32_32x32x16_bf16 v[20:35], v[148:151], v[92:95], v[20:35]
	v_exp_f32_e32 v80, v80
	v_exp_f32_e32 v81, v81
	v_exp_f32_e32 v82, v82
	v_exp_f32_e32 v83, v83
	s_waitcnt lgkmcnt(6)
	v_mfma_f32_32x32x16_bf16 v[4:19], v[140:143], v[96:99], v[4:19]
	v_exp_f32_e32 v36, v36
	v_exp_f32_e32 v37, v37
	v_exp_f32_e32 v38, v38
	v_exp_f32_e32 v39, v39
	s_waitcnt lgkmcnt(4)
	v_mfma_f32_32x32x16_bf16 v[20:35], v[140:143], v[52:55], v[20:35]
	v_exp_f32_e32 v40, v40
	v_exp_f32_e32 v41, v41
	v_exp_f32_e32 v42, v42
	v_exp_f32_e32 v43, v43
	s_waitcnt lgkmcnt(2)
	v_mfma_f32_32x32x16_bf16 v[4:19], v[132:135], v[56:59], v[4:19]
	v_exp_f32_e32 v44, v44
	v_exp_f32_e32 v45, v45
	v_exp_f32_e32 v46, v46
	v_exp_f32_e32 v47, v47
	s_waitcnt lgkmcnt(0)
	v_mfma_f32_32x32x16_bf16 v[20:35], v[132:135], v[60:63], v[20:35]
	v_exp_f32_e32 v48, v48
	v_exp_f32_e32 v49, v49
	v_exp_f32_e32 v50, v50
	v_exp_f32_e32 v51, v51
	v_add_f32_e32 v52, v68, v69
	v_add_f32_e32 v52, v70, v52
	v_add_f32_e32 v52, v71, v52
	v_add_f32_e32 v52, v72, v52
	v_add_f32_e32 v52, v73, v52
	v_add_f32_e32 v52, v74, v52
	v_add_f32_e32 v52, v75, v52
	v_add_f32_e32 v52, v76, v52
	v_add_f32_e32 v52, v77, v52
	v_add_f32_e32 v52, v78, v52
	v_add_f32_e32 v52, v79, v52
	v_add_f32_e32 v52, v80, v52
	v_add_f32_e32 v52, v81, v52
	v_add_f32_e32 v52, v82, v52
	v_add_f32_e32 v52, v83, v52
	v_add_f32_e32 v52, v36, v52
	v_add_f32_e32 v52, v37, v52
	v_add_f32_e32 v52, v38, v52
	v_add_f32_e32 v52, v39, v52
	v_add_f32_e32 v52, v40, v52
	v_add_f32_e32 v52, v41, v52
	v_add_f32_e32 v52, v42, v52
	v_add_f32_e32 v52, v43, v52
	v_add_f32_e32 v52, v44, v52
	v_add_f32_e32 v52, v45, v52
	v_add_f32_e32 v52, v46, v52
	v_add_f32_e32 v52, v47, v52
	v_add_f32_e32 v52, v48, v52
	v_add_f32_e32 v52, v49, v52
	v_add_f32_e32 v52, v50, v52
	v_add_f32_e32 v52, v51, v52
	v_add_f32_e32 v1, v1, v100
	v_add_f32_e32 v1, v1, v52
	v_cvt_pk_bf16_f32 v52, v68, v69
	v_cvt_pk_bf16_f32 v53, v70, v71
	v_cvt_pk_bf16_f32 v54, v72, v73
	v_cvt_pk_bf16_f32 v55, v74, v75
	v_cvt_pk_bf16_f32 v56, v76, v77
	v_cvt_pk_bf16_f32 v57, v78, v79
	v_cvt_pk_bf16_f32 v58, v80, v81
	v_cvt_pk_bf16_f32 v59, v82, v83
	v_cvt_pk_bf16_f32 v36, v36, v37
	v_cvt_pk_bf16_f32 v37, v38, v39
	v_cvt_pk_bf16_f32 v38, v40, v41
	v_cvt_pk_bf16_f32 v39, v42, v43
	v_cvt_pk_bf16_f32 v40, v44, v45
	v_cvt_pk_bf16_f32 v41, v46, v47
	v_cvt_pk_bf16_f32 v42, v48, v49
	v_cvt_pk_bf16_f32 v43, v50, v51
	v_add3_u32 v0, v0, v3, s24
	ds_read_b64_tr_b16 v[44:45],v0 offset:0
	ds_read_b64_tr_b16 v[46:47],v0 offset:512
	ds_read_b64_tr_b16 v[48:49],v0 offset:1024
	ds_read_b64_tr_b16 v[50:51],v0 offset:1536
	ds_read_b64_tr_b16 v[60:61],v0 offset:2048
	ds_read_b64_tr_b16 v[62:63],v0 offset:2560
	ds_read_b64_tr_b16 v[64:65],v0 offset:3072
	ds_read_b64_tr_b16 v[66:67],v0 offset:3584
	s_waitcnt lgkmcnt(0)
	s_nop 0
	v_mfma_f32_32x32x16_bf16 v[4:19], v[52:55], v[44:47], v[4:19]
	ds_read_b64_tr_b16 v[44:45],v0 offset:4096
	ds_read_b64_tr_b16 v[46:47],v0 offset:4608
	v_mfma_f32_32x32x16_bf16 v[4:19], v[56:59], v[48:51], v[4:19]
	ds_read_b64_tr_b16 v[48:49],v0 offset:5120
	ds_read_b64_tr_b16 v[50:51],v0 offset:5632
	v_mfma_f32_32x32x16_bf16 v[4:19], v[36:39], v[60:63], v[4:19]
	ds_read_b64_tr_b16 v[60:61],v0 offset:6144
	ds_read_b64_tr_b16 v[62:63],v0 offset:6656
	v_mfma_f32_32x32x16_bf16 v[4:19], v[40:43], v[64:67], v[4:19]
	ds_read_b64_tr_b16 v[64:65],v0 offset:7168
	ds_read_b64_tr_b16 v[66:67],v0 offset:7680
	s_waitcnt lgkmcnt(0)
	v_mfma_f32_32x32x16_bf16 v[20:35], v[52:55], v[44:47], v[20:35]
	v_mfma_f32_32x32x16_bf16 v[20:35], v[56:59], v[48:51], v[20:35]
	v_mfma_f32_32x32x16_bf16 v[20:35], v[36:39], v[60:63], v[20:35]
	v_mfma_f32_32x32x16_bf16 v[20:35], v[40:43], v[64:67], v[20:35]
	s_setprio 0
	v_mov_b32_e32 v0, v1
	s_nop 1
	v_permlane32_swap_b32_e32 v1, v0
	v_cmp_gt_u32_e32 vcc, 32, v186
	s_and_saveexec_b64 s[24:25], vcc
	s_cbranch_execz .LBB0_727
	v_lshl_add_u32 v3, v188, 2, s28
	v_add_f32_e32 v0, v1, v0
	ds_write_b32 v3, v0 offset:49280
	s_branch .LBB0_727
